# swiglu epilogue: 8 row-scale loads issued up front, 7 vmcnt(0) after stores removed (P2,P11)
# speedup vs baseline: 1.0045x; 1.0045x over previous
.LBB0_216:
	v_lshl_or_b32 v172, s92, 7, v155
	v_ashrrev_i32_e32 v173, 31, v172
	v_lshlrev_b64 v[146:147], 2, v[172:173]
	v_lshl_add_u64 v[152:153], s[80:81], 0, v[146:147]
	v_lshl_add_u64 v[146:147], s[36:37], 0, v[146:147]
	global_load_dwordx4 v[148:151], v[152:153], off
	global_load_dwordx4 v[160:163], v[152:153], off offset:16
	global_load_dwordx4 v[164:167], v[146:147], off
	global_load_dwordx4 v[168:171], v[146:147], off offset:16
	v_lshl_add_u32 v146, s82, 8, v1
	v_ashrrev_i32_e32 v147, 31, v146
	v_lshl_add_u64 v[152:153], v[146:147], 2, s[70:71]
	global_load_dword v174, v[152:153], off
	global_load_dword v192, v[152:153], off offset:64
	global_load_dword v193, v[152:153], off offset:128
	global_load_dword v194, v[152:153], off offset:192
	global_load_dword v195, v[152:153], off offset:512
	global_load_dword v196, v[152:153], off offset:576
	global_load_dword v197, v[152:153], off offset:640
	global_load_dword v198, v[152:153], off offset:704
	v_cvt_f32_i32_e32 v177, v127
	v_cvt_f32_i32_e32 v176, v126
	v_cvt_f32_i32_e32 v185, v119
	v_cvt_f32_i32_e32 v184, v118
	v_cvt_f32_i32_e32 v179, v129
	v_cvt_f32_i32_e32 v178, v128
	v_cvt_f32_i32_e32 v187, v121
	v_cvt_f32_i32_e32 v186, v120
	v_cvt_f32_i32_e32 v189, v115
	v_cvt_f32_i32_e32 v188, v114
	v_mov_b64_e32 v[114:115], s[38:39]
	v_cvt_f32_i32_e32 v191, v117
	v_cvt_f32_i32_e32 v190, v116
	v_mad_i64_i32 v[118:119], s[8:9], v146, s91, v[114:115]
	v_lshlrev_b64 v[116:117], 1, v[172:173]
	v_cvt_f32_i32_e32 v181, v123
	v_cvt_f32_i32_e32 v180, v122
	v_lshl_add_u64 v[172:173], v[118:119], 0, v[116:117]
	v_cvt_f32_i32_e32 v183, v125
	v_cvt_f32_i32_e32 v182, v124
	v_cvt_f32_i32_e32 v111, v111
	v_cvt_f32_i32_e32 v110, v110
	v_cvt_f32_i32_e32 v103, v103
	v_cvt_f32_i32_e32 v102, v102
	v_cvt_f32_i32_e32 v113, v113
	v_cvt_f32_i32_e32 v112, v112
	v_cvt_f32_i32_e32 v107, v107
	v_cvt_f32_i32_e32 v106, v106
	v_cvt_f32_i32_e32 v99, v99
	v_cvt_f32_i32_e32 v98, v98
	v_cvt_f32_i32_e32 v101, v101
	v_cvt_f32_i32_e32 v100, v100
	v_cvt_f32_i32_e32 v109, v109
	v_cvt_f32_i32_e32 v108, v108
	v_cvt_f32_i32_e32 v105, v105
	v_cvt_f32_i32_e32 v104, v104
	v_cvt_f32_i32_e32 v95, v95
	v_cvt_f32_i32_e32 v94, v94
	v_cvt_f32_i32_e32 v87, v87
	v_cvt_f32_i32_e32 v86, v86
	v_cvt_f32_i32_e32 v97, v97
	v_cvt_f32_i32_e32 v96, v96
	v_cvt_f32_i32_e32 v91, v91
	v_cvt_f32_i32_e32 v90, v90
	v_cvt_f32_i32_e32 v83, v83
	v_cvt_f32_i32_e32 v82, v82
	v_cvt_f32_i32_e32 v85, v85
	v_cvt_f32_i32_e32 v84, v84
	v_cvt_f32_i32_e32 v93, v93
	v_cvt_f32_i32_e32 v92, v92
	v_cvt_f32_i32_e32 v89, v89
	v_cvt_f32_i32_e32 v88, v88
	v_cvt_f32_i32_e32 v79, v79
	v_cvt_f32_i32_e32 v78, v78
	v_cvt_f32_i32_e32 v81, v81
	v_cvt_f32_i32_e32 v80, v80
	v_cvt_f32_i32_e32 v71, v71
	v_cvt_f32_i32_e32 v70, v70
	v_cvt_f32_i32_e32 v75, v75
	v_cvt_f32_i32_e32 v74, v74
	v_cvt_f32_i32_e32 v67, v67
	v_cvt_f32_i32_e32 v66, v66
	v_cvt_f32_i32_e32 v69, v69
	v_cvt_f32_i32_e32 v68, v68
	v_cvt_f32_i32_e32 v77, v77
	v_cvt_f32_i32_e32 v76, v76
	v_cvt_f32_i32_e32 v73, v73
	v_cvt_f32_i32_e32 v72, v72
	v_cvt_f32_i32_e32 v63, v63
	v_cvt_f32_i32_e32 v62, v62
	v_cvt_f32_i32_e32 v65, v65
	v_cvt_f32_i32_e32 v64, v64
	s_waitcnt vmcnt(0)
	v_pk_mul_f32 v[120:121], v[148:149], s[40:41] op_sel_hi:[1,0]
	v_pk_mul_f32 v[128:129], v[164:165], s[40:41] op_sel_hi:[1,0]
	v_pk_mul_f32 v[118:119], v[150:151], s[40:41] op_sel_hi:[1,0]
	v_pk_mul_f32 v[122:123], v[162:163], s[40:41] op_sel_hi:[1,0]
	v_pk_mul_f32 v[126:127], v[166:167], s[40:41] op_sel_hi:[1,0]
	v_pk_mul_f32 v[148:149], v[170:171], s[40:41] op_sel_hi:[1,0]
	v_pk_mul_f32 v[162:163], v[120:121], v[176:177]
	v_pk_mul_f32 v[170:171], v[128:129], v[184:185]
	v_pk_mul_f32 v[124:125], v[160:161], s[40:41] op_sel_hi:[1,0]
	v_pk_mul_f32 v[150:151], v[168:169], s[40:41] op_sel_hi:[1,0]
	v_pk_mul_f32 v[160:161], v[118:119], v[178:179]
	v_pk_mul_f32 v[168:169], v[126:127], v[186:187]
	v_pk_mul_f32 v[162:163], v[162:163], v[174:175] op_sel_hi:[1,0]
	v_pk_mul_f32 v[170:171], v[170:171], v[174:175] op_sel_hi:[1,0]
	v_pk_mul_f32 v[160:161], v[160:161], v[174:175] op_sel_hi:[1,0]
	v_pk_mul_f32 v[168:169], v[168:169], v[174:175] op_sel_hi:[1,0]
	v_mul_f32_e32 v147, v162, v170
	v_mul_f32_e32 v159, 0xbfb8aa3b, v162
	v_mul_f32_e32 v162, v163, v171
	v_mul_f32_e32 v163, 0xbfb8aa3b, v163
	v_mul_f32_e32 v168, v160, v168
	v_mul_f32_e32 v160, 0xbfb8aa3b, v160
	v_exp_f32_e32 v159, v159
	v_exp_f32_e32 v163, v163
	v_exp_f32_e32 v160, v160
	v_pk_mul_f32 v[164:165], v[122:123], v[182:183]
	v_pk_mul_f32 v[166:167], v[124:125], v[180:181]
	v_pk_mul_f32 v[176:177], v[148:149], v[190:191]
	v_pk_mul_f32 v[178:179], v[150:151], v[188:189]
	v_add_f32_e32 v159, 1.0, v159
	v_add_f32_e32 v163, 1.0, v163
	v_pk_mul_f32 v[164:165], v[164:165], v[174:175] op_sel_hi:[1,0]
	v_pk_mul_f32 v[166:167], v[166:167], v[174:175] op_sel_hi:[1,0]
	v_pk_mul_f32 v[176:177], v[176:177], v[174:175] op_sel_hi:[1,0]
	v_pk_mul_f32 v[174:175], v[178:179], v[174:175] op_sel_hi:[1,0]
	v_add_f32_e32 v160, 1.0, v160
	v_rcp_f32_e32 v159, v159
	v_rcp_f32_e32 v163, v163
	v_mul_f32_e32 v169, v161, v169
	v_mul_f32_e32 v161, 0xbfb8aa3b, v161
	v_mul_f32_e32 v170, v166, v174
	v_mul_f32_e32 v166, 0xbfb8aa3b, v166
	v_mul_f32_e32 v171, v167, v175
	v_mul_f32_e32 v167, 0xbfb8aa3b, v167
	v_rcp_f32_e32 v160, v160
	v_exp_f32_e32 v161, v161
	v_exp_f32_e32 v166, v166
	v_exp_f32_e32 v167, v167
	v_mul_f32_e32 v174, 0xbfb8aa3b, v164
	v_mul_f32_e32 v175, 0xbfb8aa3b, v165
	v_exp_f32_e32 v174, v174
	v_mul_f32_e32 v147, v147, v159
	v_mul_f32_e32 v159, v162, v163
	v_mul_f32_e32 v162, v168, v160
	v_cvt_pkrtz_f16_f32 v160, v147, v159
	v_exp_f32_e32 v147, v175
	v_add_f32_e32 v161, 1.0, v161
	v_add_f32_e32 v166, 1.0, v166
	v_add_f32_e32 v167, 1.0, v167
	v_rcp_f32_e32 v161, v161
	v_rcp_f32_e32 v166, v166
	v_rcp_f32_e32 v167, v167
	v_add_f32_e32 v159, 1.0, v174
	v_rcp_f32_e32 v159, v159
	v_add_f32_e32 v147, 1.0, v147
	v_rcp_f32_e32 v147, v147
	v_mul_f32_e32 v161, v169, v161
	v_mul_f32_e32 v163, v170, v166
	v_mul_f32_e32 v166, v171, v167
	v_cvt_pkrtz_f16_f32 v161, v162, v161
	v_cvt_pkrtz_f16_f32 v162, v163, v166
	v_mul_f32_e32 v163, v164, v176
	v_mul_f32_e32 v159, v163, v159
	v_mul_f32_e32 v163, v165, v177
	v_mul_f32_e32 v147, v163, v147
	v_cvt_pkrtz_f16_f32 v163, v159, v147
	global_store_dwordx4 v[172:173], v[160:163], off
	v_pk_mul_f32 v[110:111], v[120:121], v[110:111]
	v_pk_mul_f32 v[102:103], v[128:129], v[102:103]
	v_or_b32_e32 v160, 16, v146
	v_ashrrev_i32_e32 v161, 31, v160
	v_lshl_add_u64 v[162:163], v[160:161], 2, s[70:71]
	v_mov_b32_e32 v162, v192
	v_pk_mul_f32 v[112:113], v[118:119], v[112:113]
	v_pk_mul_f32 v[106:107], v[124:125], v[106:107]
	v_pk_mul_f32 v[100:101], v[148:149], v[100:101]
	v_pk_mul_f32 v[98:99], v[150:151], v[98:99]
	v_pk_mul_f32 v[108:109], v[122:123], v[108:109]
	v_pk_mul_f32 v[104:105], v[126:127], v[104:105]
	v_mad_i64_i32 v[160:161], s[8:9], v160, s91, v[114:115]
	v_lshl_add_u64 v[160:161], v[160:161], 0, v[116:117]
	v_pk_mul_f32 v[94:95], v[120:121], v[94:95]
	v_pk_mul_f32 v[86:87], v[128:129], v[86:87]
	v_pk_mul_f32 v[96:97], v[118:119], v[96:97]
	v_pk_mul_f32 v[90:91], v[124:125], v[90:91]
	v_pk_mul_f32 v[84:85], v[148:149], v[84:85]
	v_pk_mul_f32 v[82:83], v[150:151], v[82:83]
	v_pk_mul_f32 v[92:93], v[122:123], v[92:93]
	v_pk_mul_f32 v[88:89], v[126:127], v[88:89]
	v_pk_mul_f32 v[80:81], v[118:119], v[80:81]
	v_pk_mul_f32 v[78:79], v[120:121], v[78:79]
	v_pk_mul_f32 v[70:71], v[128:129], v[70:71]
	v_pk_mul_f32 v[74:75], v[124:125], v[74:75]
	v_pk_mul_f32 v[68:69], v[148:149], v[68:69]
	v_pk_mul_f32 v[66:67], v[150:151], v[66:67]
	v_pk_mul_f32 v[76:77], v[122:123], v[76:77]
	v_pk_mul_f32 v[72:73], v[126:127], v[72:73]
	v_cvt_f32_i32_e32 v59, v59
	v_cvt_f32_i32_e32 v58, v58
	v_cvt_f32_i32_e32 v61, v61
	v_cvt_f32_i32_e32 v60, v60
	v_cvt_f32_i32_e32 v55, v55
	v_cvt_f32_i32_e32 v54, v54
	v_cvt_f32_i32_e32 v57, v57
	v_cvt_f32_i32_e32 v56, v56
	v_cvt_f32_i32_e32 v51, v51
	v_cvt_f32_i32_e32 v50, v50
	v_cvt_f32_i32_e32 v53, v53
	v_cvt_f32_i32_e32 v52, v52
	v_pk_mul_f32 v[64:65], v[118:119], v[64:65]
	v_pk_mul_f32 v[62:63], v[120:121], v[62:63]
	v_pk_mul_f32 v[60:61], v[122:123], v[60:61]
	v_pk_mul_f32 v[58:59], v[124:125], v[58:59]
	v_pk_mul_f32 v[56:57], v[126:127], v[56:57]
	v_pk_mul_f32 v[54:55], v[128:129], v[54:55]
	v_pk_mul_f32 v[52:53], v[148:149], v[52:53]
	v_pk_mul_f32 v[50:51], v[150:151], v[50:51]
	v_cvt_f32_i32_e32 v47, v47
	v_cvt_f32_i32_e32 v46, v46
	v_cvt_f32_i32_e32 v49, v49
	v_cvt_f32_i32_e32 v48, v48
	v_cvt_f32_i32_e32 v43, v43
	v_cvt_f32_i32_e32 v42, v42
	v_cvt_f32_i32_e32 v45, v45
	v_cvt_f32_i32_e32 v44, v44
	v_cvt_f32_i32_e32 v39, v39
	v_cvt_f32_i32_e32 v38, v38
	v_cvt_f32_i32_e32 v41, v41
	v_cvt_f32_i32_e32 v40, v40
	v_cvt_f32_i32_e32 v35, v35
	v_cvt_f32_i32_e32 v34, v34
	v_cvt_f32_i32_e32 v37, v37
	v_cvt_f32_i32_e32 v36, v36
	v_pk_mul_f32 v[48:49], v[118:119], v[48:49]
	v_pk_mul_f32 v[46:47], v[120:121], v[46:47]
	v_pk_mul_f32 v[44:45], v[122:123], v[44:45]
	v_pk_mul_f32 v[42:43], v[124:125], v[42:43]
	v_pk_mul_f32 v[40:41], v[126:127], v[40:41]
	v_pk_mul_f32 v[38:39], v[128:129], v[38:39]
	v_pk_mul_f32 v[36:37], v[148:149], v[36:37]
	v_pk_mul_f32 v[34:35], v[150:151], v[34:35]
	v_cvt_f32_i32_e32 v31, v31
	v_cvt_f32_i32_e32 v30, v30
	v_cvt_f32_i32_e32 v33, v33
	v_cvt_f32_i32_e32 v32, v32
	v_cvt_f32_i32_e32 v27, v27
	v_cvt_f32_i32_e32 v26, v26
	v_cvt_f32_i32_e32 v29, v29
	v_cvt_f32_i32_e32 v28, v28
	v_cvt_f32_i32_e32 v23, v23
	v_cvt_f32_i32_e32 v22, v22
	v_pk_mul_f32 v[110:111], v[110:111], v[162:163] op_sel_hi:[1,0]
	v_pk_mul_f32 v[102:103], v[102:103], v[162:163] op_sel_hi:[1,0]
	v_pk_mul_f32 v[112:113], v[112:113], v[162:163] op_sel_hi:[1,0]
	v_pk_mul_f32 v[106:107], v[106:107], v[162:163] op_sel_hi:[1,0]
	v_pk_mul_f32 v[164:165], v[100:101], v[162:163] op_sel_hi:[1,0]
	v_pk_mul_f32 v[98:99], v[98:99], v[162:163] op_sel_hi:[1,0]
	v_mul_f32_e32 v100, v110, v102
	v_mul_f32_e32 v101, 0xbfb8aa3b, v110
	v_mul_f32_e32 v102, v111, v103
	v_mul_f32_e32 v103, 0xbfb8aa3b, v111
	v_mul_f32_e32 v110, 0xbfb8aa3b, v112
	v_mul_f32_e32 v111, 0xbfb8aa3b, v113
	v_mul_f32_e32 v98, v106, v98
	v_mul_f32_e32 v106, 0xbfb8aa3b, v106
	v_exp_f32_e32 v101, v101
	v_exp_f32_e32 v103, v103
	v_mul_f32_e32 v99, v107, v99
	v_mul_f32_e32 v107, 0xbfb8aa3b, v107
	v_exp_f32_e32 v110, v110
	v_exp_f32_e32 v111, v111
	v_exp_f32_e32 v106, v106
	v_exp_f32_e32 v107, v107
	v_pk_mul_f32 v[108:109], v[108:109], v[162:163] op_sel_hi:[1,0]
	v_pk_mul_f32 v[104:105], v[104:105], v[162:163] op_sel_hi:[1,0]
	v_add_f32_e32 v101, 1.0, v101
	v_add_f32_e32 v103, 1.0, v103
	v_mul_f32_e32 v104, v112, v104
	v_mul_f32_e32 v112, 0xbfb8aa3b, v108
	v_add_f32_e32 v110, 1.0, v110
	v_add_f32_e32 v111, 1.0, v111
	v_add_f32_e32 v106, 1.0, v106
	v_rcp_f32_e32 v101, v101
	v_rcp_f32_e32 v103, v103
	v_mul_f32_e32 v105, v113, v105
	v_mul_f32_e32 v113, 0xbfb8aa3b, v109
	v_exp_f32_e32 v112, v112
	v_add_f32_e32 v107, 1.0, v107
	v_rcp_f32_e32 v110, v110
	v_rcp_f32_e32 v111, v111
	v_rcp_f32_e32 v106, v106
	v_exp_f32_e32 v113, v113
	v_rcp_f32_e32 v107, v107
	v_mul_f32_e32 v100, v100, v101
	v_mul_f32_e32 v101, v102, v103
	v_mul_f32_e32 v102, v104, v110
	v_mul_f32_e32 v103, v105, v111
	v_mul_f32_e32 v104, v98, v106
	v_cvt_pkrtz_f16_f32 v98, v100, v101
	v_add_f32_e32 v101, 1.0, v112
	v_mul_f32_e32 v105, v99, v107
	v_cvt_pkrtz_f16_f32 v99, v102, v103
	v_rcp_f32_e32 v101, v101
	v_add_f32_e32 v102, 1.0, v113
	v_rcp_f32_e32 v102, v102
	v_mul_f32_e32 v103, v108, v164
	v_mul_f32_e32 v101, v103, v101
	v_mul_f32_e32 v103, v109, v165
	v_mul_f32_e32 v102, v103, v102
	v_cvt_pkrtz_f16_f32 v100, v104, v105
	v_cvt_pkrtz_f16_f32 v101, v101, v102
	global_store_dwordx4 v[160:161], v[98:101], off
	v_cvt_f32_i32_e32 v25, v25
	v_cvt_f32_i32_e32 v24, v24
	v_or_b32_e32 v98, 32, v146
	v_ashrrev_i32_e32 v99, 31, v98
	v_lshl_add_u64 v[100:101], v[98:99], 2, s[70:71]
	v_mov_b32_e32 v100, v193
	v_mad_i64_i32 v[98:99], s[8:9], v98, s91, v[114:115]
	v_lshl_add_u64 v[98:99], v[98:99], 0, v[116:117]
	v_cvt_f32_i32_e32 v19, v19
	v_cvt_f32_i32_e32 v18, v18
	v_cvt_f32_i32_e32 v21, v21
	v_cvt_f32_i32_e32 v20, v20
	v_pk_mul_f32 v[32:33], v[118:119], v[32:33]
	v_pk_mul_f32 v[30:31], v[120:121], v[30:31]
	v_pk_mul_f32 v[28:29], v[122:123], v[28:29]
	v_pk_mul_f32 v[26:27], v[124:125], v[26:27]
	v_pk_mul_f32 v[24:25], v[126:127], v[24:25]
	v_pk_mul_f32 v[22:23], v[128:129], v[22:23]
	v_pk_mul_f32 v[20:21], v[148:149], v[20:21]
	v_pk_mul_f32 v[18:19], v[150:151], v[18:19]
	v_cvt_f32_i32_e32 v15, v15
	v_cvt_f32_i32_e32 v14, v14
	v_cvt_f32_i32_e32 v17, v17
	v_cvt_f32_i32_e32 v16, v16
	v_cvt_f32_i32_e32 v11, v11
	v_cvt_f32_i32_e32 v10, v10
	v_cvt_f32_i32_e32 v13, v13
	v_cvt_f32_i32_e32 v12, v12
	v_cvt_f32_i32_e32 v7, v7
	v_cvt_f32_i32_e32 v6, v6
	v_cvt_f32_i32_e32 v9, v9
	v_cvt_f32_i32_e32 v8, v8
	v_cvt_f32_i32_e32 v3, v3
	v_cvt_f32_i32_e32 v2, v2
	v_cvt_f32_i32_e32 v5, v5
	v_cvt_f32_i32_e32 v4, v4
	v_pk_mul_f32 v[16:17], v[118:119], v[16:17]
	v_pk_mul_f32 v[14:15], v[120:121], v[14:15]
	v_pk_mul_f32 v[12:13], v[122:123], v[12:13]
	v_pk_mul_f32 v[10:11], v[124:125], v[10:11]
	v_pk_mul_f32 v[8:9], v[126:127], v[8:9]
	v_pk_mul_f32 v[6:7], v[128:129], v[6:7]
	v_pk_mul_f32 v[4:5], v[148:149], v[4:5]
	v_pk_mul_f32 v[2:3], v[150:151], v[2:3]
	s_andn2_b64 vcc, exec, s[2:3]
	s_mov_b64 s[2:3], -1
	v_pk_mul_f32 v[94:95], v[94:95], v[100:101] op_sel_hi:[1,0]
	v_pk_mul_f32 v[86:87], v[86:87], v[100:101] op_sel_hi:[1,0]
	v_pk_mul_f32 v[96:97], v[96:97], v[100:101] op_sel_hi:[1,0]
	v_pk_mul_f32 v[90:91], v[90:91], v[100:101] op_sel_hi:[1,0]
	v_pk_mul_f32 v[102:103], v[84:85], v[100:101] op_sel_hi:[1,0]
	v_pk_mul_f32 v[82:83], v[82:83], v[100:101] op_sel_hi:[1,0]
	v_mul_f32_e32 v84, v94, v86
	v_mul_f32_e32 v85, 0xbfb8aa3b, v94
	v_mul_f32_e32 v86, v95, v87
	v_mul_f32_e32 v87, 0xbfb8aa3b, v95
	v_mul_f32_e32 v94, 0xbfb8aa3b, v96
	v_mul_f32_e32 v82, v90, v82
	v_mul_f32_e32 v90, 0xbfb8aa3b, v90
	v_exp_f32_e32 v85, v85
	v_exp_f32_e32 v87, v87
	v_exp_f32_e32 v94, v94
	v_exp_f32_e32 v90, v90
	v_mul_f32_e32 v95, 0xbfb8aa3b, v97
	v_pk_mul_f32 v[92:93], v[92:93], v[100:101] op_sel_hi:[1,0]
	v_pk_mul_f32 v[88:89], v[88:89], v[100:101] op_sel_hi:[1,0]
	v_mul_f32_e32 v83, v91, v83
	v_mul_f32_e32 v91, 0xbfb8aa3b, v91
	v_exp_f32_e32 v95, v95
	v_add_f32_e32 v85, 1.0, v85
	v_add_f32_e32 v87, 1.0, v87
	v_mul_f32_e32 v88, v96, v88
	v_mul_f32_e32 v89, v97, v89
	v_mul_f32_e32 v96, 0xbfb8aa3b, v92
	v_mul_f32_e32 v97, 0xbfb8aa3b, v93
	v_exp_f32_e32 v91, v91
	v_add_f32_e32 v94, 1.0, v94
	v_add_f32_e32 v90, 1.0, v90
	v_rcp_f32_e32 v85, v85
	v_rcp_f32_e32 v87, v87
	v_exp_f32_e32 v96, v96
	v_exp_f32_e32 v97, v97
	v_rcp_f32_e32 v94, v94
	v_rcp_f32_e32 v90, v90
	v_add_f32_e32 v95, 1.0, v95
	v_add_f32_e32 v91, 1.0, v91
	v_rcp_f32_e32 v95, v95
	v_mul_f32_e32 v84, v84, v85
	v_mul_f32_e32 v85, v86, v87
	v_add_f32_e32 v96, 1.0, v96
	v_rcp_f32_e32 v91, v91
	v_mul_f32_e32 v86, v88, v94
	v_mul_f32_e32 v88, v82, v90
	v_cvt_pkrtz_f16_f32 v82, v84, v85
	v_add_f32_e32 v85, 1.0, v97
	v_rcp_f32_e32 v96, v96
	v_rcp_f32_e32 v85, v85
	v_mul_f32_e32 v87, v89, v95
	v_mul_f32_e32 v89, v83, v91
	v_cvt_pkrtz_f16_f32 v83, v86, v87
	v_mul_f32_e32 v86, v92, v102
	v_mul_f32_e32 v87, v93, v103
	v_mul_f32_e32 v86, v86, v96
	v_mul_f32_e32 v85, v87, v85
	v_cvt_pkrtz_f16_f32 v84, v88, v89
	v_cvt_pkrtz_f16_f32 v85, v86, v85
	global_store_dwordx4 v[98:99], v[82:85], off
	s_nop 1
	v_or_b32_e32 v82, 48, v146
	v_ashrrev_i32_e32 v83, 31, v82
	v_lshl_add_u64 v[84:85], v[82:83], 2, s[70:71]
	v_mov_b32_e32 v84, v194
	v_mad_i64_i32 v[82:83], s[8:9], v82, s91, v[114:115]
	v_lshl_add_u64 v[82:83], v[82:83], 0, v[116:117]
	v_pk_mul_f32 v[80:81], v[80:81], v[84:85] op_sel_hi:[1,0]
	v_pk_mul_f32 v[78:79], v[78:79], v[84:85] op_sel_hi:[1,0]
	v_pk_mul_f32 v[70:71], v[70:71], v[84:85] op_sel_hi:[1,0]
	v_pk_mul_f32 v[74:75], v[74:75], v[84:85] op_sel_hi:[1,0]
	v_pk_mul_f32 v[86:87], v[68:69], v[84:85] op_sel_hi:[1,0]
	v_pk_mul_f32 v[66:67], v[66:67], v[84:85] op_sel_hi:[1,0]
	v_mul_f32_e32 v68, v78, v70
	v_mul_f32_e32 v69, 0xbfb8aa3b, v78
	v_mul_f32_e32 v70, v79, v71
	v_mul_f32_e32 v71, 0xbfb8aa3b, v79
	v_mul_f32_e32 v78, 0xbfb8aa3b, v80
	v_mul_f32_e32 v79, 0xbfb8aa3b, v81
	v_pk_mul_f32 v[76:77], v[76:77], v[84:85] op_sel_hi:[1,0]
	v_pk_mul_f32 v[72:73], v[72:73], v[84:85] op_sel_hi:[1,0]
	v_mul_f32_e32 v66, v74, v66
	v_mul_f32_e32 v74, 0xbfb8aa3b, v74
	v_mul_f32_e32 v67, v75, v67
	v_mul_f32_e32 v75, 0xbfb8aa3b, v75
	v_exp_f32_e32 v69, v69
	v_exp_f32_e32 v71, v71
	v_exp_f32_e32 v78, v78
	v_exp_f32_e32 v79, v79
	v_mul_f32_e32 v72, v80, v72
	v_mul_f32_e32 v73, v81, v73
	v_mul_f32_e32 v80, 0xbfb8aa3b, v76
	v_mul_f32_e32 v81, 0xbfb8aa3b, v77
	v_exp_f32_e32 v74, v74
	v_exp_f32_e32 v75, v75
	v_exp_f32_e32 v80, v80
	v_exp_f32_e32 v81, v81
	v_add_f32_e32 v69, 1.0, v69
	v_add_f32_e32 v71, 1.0, v71
	v_add_f32_e32 v78, 1.0, v78
	v_add_f32_e32 v79, 1.0, v79
	v_add_f32_e32 v74, 1.0, v74
	v_add_f32_e32 v75, 1.0, v75
	v_rcp_f32_e32 v69, v69
	v_rcp_f32_e32 v71, v71
	v_rcp_f32_e32 v78, v78
	v_rcp_f32_e32 v79, v79
	v_add_f32_e32 v80, 1.0, v80
	v_add_f32_e32 v81, 1.0, v81
	v_rcp_f32_e32 v74, v74
	v_rcp_f32_e32 v75, v75
	v_rcp_f32_e32 v80, v80
	v_rcp_f32_e32 v81, v81
	v_mul_f32_e32 v68, v68, v69
	v_mul_f32_e32 v69, v70, v71
	v_mul_f32_e32 v70, v72, v78
	v_mul_f32_e32 v71, v73, v79
	v_mul_f32_e32 v72, v66, v74
	v_mul_f32_e32 v73, v67, v75
	v_cvt_pkrtz_f16_f32 v66, v68, v69
	v_cvt_pkrtz_f16_f32 v67, v70, v71
	v_mul_f32_e32 v69, v76, v86
	v_mul_f32_e32 v70, v77, v87
	v_mul_f32_e32 v69, v69, v80
	v_mul_f32_e32 v70, v70, v81
	v_cvt_pkrtz_f16_f32 v68, v72, v73
	v_cvt_pkrtz_f16_f32 v69, v69, v70
	global_store_dwordx4 v[82:83], v[66:69], off
	s_nop 1
	v_mov_b32_e32 v66, v195
	v_add_u32_e32 v67, 0x80, v146
	v_mad_i64_i32 v[68:69], s[8:9], v67, s91, v[114:115]
	v_lshl_add_u64 v[68:69], v[68:69], 0, v[116:117]
	v_pk_mul_f32 v[64:65], v[64:65], v[66:67] op_sel_hi:[1,0]
	v_pk_mul_f32 v[62:63], v[62:63], v[66:67] op_sel_hi:[1,0]
	v_pk_mul_f32 v[60:61], v[60:61], v[66:67] op_sel_hi:[1,0]
	v_pk_mul_f32 v[58:59], v[58:59], v[66:67] op_sel_hi:[1,0]
	v_pk_mul_f32 v[56:57], v[56:57], v[66:67] op_sel_hi:[1,0]
	v_pk_mul_f32 v[54:55], v[54:55], v[66:67] op_sel_hi:[1,0]
	v_pk_mul_f32 v[52:53], v[52:53], v[66:67] op_sel_hi:[1,0]
	v_pk_mul_f32 v[50:51], v[50:51], v[66:67] op_sel_hi:[1,0]
	v_mul_f32_e32 v54, v62, v54
	v_mul_f32_e32 v62, 0xbfb8aa3b, v62
	v_mul_f32_e32 v55, v63, v55
	v_mul_f32_e32 v63, 0xbfb8aa3b, v63
	v_mul_f32_e32 v56, v64, v56
	v_mul_f32_e32 v64, 0xbfb8aa3b, v64
	v_mul_f32_e32 v57, v65, v57
	v_mul_f32_e32 v65, 0xbfb8aa3b, v65
	v_mul_f32_e32 v50, v58, v50
	v_mul_f32_e32 v58, 0xbfb8aa3b, v58
	v_mul_f32_e32 v51, v59, v51
	v_mul_f32_e32 v59, 0xbfb8aa3b, v59
	v_mul_f32_e32 v52, v60, v52
	v_mul_f32_e32 v60, 0xbfb8aa3b, v60
	v_mul_f32_e32 v53, v61, v53
	v_mul_f32_e32 v61, 0xbfb8aa3b, v61
	v_exp_f32_e32 v62, v62
	v_exp_f32_e32 v63, v63
	v_exp_f32_e32 v64, v64
	v_exp_f32_e32 v65, v65
	v_exp_f32_e32 v58, v58
	v_exp_f32_e32 v59, v59
	v_exp_f32_e32 v60, v60
	v_exp_f32_e32 v61, v61
	v_add_f32_e32 v62, 1.0, v62
	v_add_f32_e32 v63, 1.0, v63
	v_add_f32_e32 v64, 1.0, v64
	v_add_f32_e32 v65, 1.0, v65
	v_add_f32_e32 v58, 1.0, v58
	v_add_f32_e32 v59, 1.0, v59
	v_add_f32_e32 v60, 1.0, v60
	v_add_f32_e32 v61, 1.0, v61
	v_rcp_f32_e32 v62, v62
	v_rcp_f32_e32 v63, v63
	v_rcp_f32_e32 v64, v64
	v_rcp_f32_e32 v65, v65
	v_rcp_f32_e32 v58, v58
	v_rcp_f32_e32 v59, v59
	v_rcp_f32_e32 v60, v60
	v_rcp_f32_e32 v61, v61
	v_mul_f32_e32 v54, v54, v62
	v_mul_f32_e32 v55, v55, v63
	v_mul_f32_e32 v56, v56, v64
	v_mul_f32_e32 v57, v57, v65
	v_mul_f32_e32 v58, v50, v58
	v_mul_f32_e32 v59, v51, v59
	v_mul_f32_e32 v60, v52, v60
	v_mul_f32_e32 v53, v53, v61
	v_cvt_pkrtz_f16_f32 v50, v54, v55
	v_cvt_pkrtz_f16_f32 v51, v56, v57
	v_cvt_pkrtz_f16_f32 v52, v58, v59
	v_cvt_pkrtz_f16_f32 v53, v60, v53
	global_store_dwordx4 v[68:69], v[50:53], off
	s_nop 1
	v_mov_b32_e32 v50, v196
	v_add_u32_e32 v51, 0x90, v146
	v_mad_i64_i32 v[52:53], s[8:9], v51, s91, v[114:115]
	v_lshl_add_u64 v[52:53], v[52:53], 0, v[116:117]
	v_pk_mul_f32 v[48:49], v[48:49], v[50:51] op_sel_hi:[1,0]
	v_pk_mul_f32 v[46:47], v[46:47], v[50:51] op_sel_hi:[1,0]
	v_pk_mul_f32 v[44:45], v[44:45], v[50:51] op_sel_hi:[1,0]
	v_pk_mul_f32 v[42:43], v[42:43], v[50:51] op_sel_hi:[1,0]
	v_pk_mul_f32 v[40:41], v[40:41], v[50:51] op_sel_hi:[1,0]
	v_pk_mul_f32 v[38:39], v[38:39], v[50:51] op_sel_hi:[1,0]
	v_pk_mul_f32 v[36:37], v[36:37], v[50:51] op_sel_hi:[1,0]
	v_pk_mul_f32 v[34:35], v[34:35], v[50:51] op_sel_hi:[1,0]
	v_mul_f32_e32 v38, v46, v38
	v_mul_f32_e32 v46, 0xbfb8aa3b, v46
	v_mul_f32_e32 v39, v47, v39
	v_mul_f32_e32 v47, 0xbfb8aa3b, v47
	v_mul_f32_e32 v40, v48, v40
	v_mul_f32_e32 v48, 0xbfb8aa3b, v48
	v_mul_f32_e32 v41, v49, v41
	v_mul_f32_e32 v49, 0xbfb8aa3b, v49
	v_mul_f32_e32 v34, v42, v34
	v_mul_f32_e32 v42, 0xbfb8aa3b, v42
	v_mul_f32_e32 v35, v43, v35
	v_mul_f32_e32 v43, 0xbfb8aa3b, v43
	v_mul_f32_e32 v36, v44, v36
	v_mul_f32_e32 v44, 0xbfb8aa3b, v44
	v_mul_f32_e32 v37, v45, v37
	v_mul_f32_e32 v45, 0xbfb8aa3b, v45
	v_exp_f32_e32 v46, v46
	v_exp_f32_e32 v47, v47
	v_exp_f32_e32 v48, v48
	v_exp_f32_e32 v49, v49
	v_exp_f32_e32 v42, v42
	v_exp_f32_e32 v43, v43
	v_exp_f32_e32 v44, v44
	v_exp_f32_e32 v45, v45
	v_add_f32_e32 v46, 1.0, v46
	v_add_f32_e32 v47, 1.0, v47
	v_add_f32_e32 v48, 1.0, v48
	v_add_f32_e32 v49, 1.0, v49
	v_add_f32_e32 v42, 1.0, v42
	v_add_f32_e32 v43, 1.0, v43
	v_add_f32_e32 v44, 1.0, v44
	v_add_f32_e32 v45, 1.0, v45
	v_rcp_f32_e32 v46, v46
	v_rcp_f32_e32 v47, v47
	v_rcp_f32_e32 v48, v48
	v_rcp_f32_e32 v49, v49
	v_rcp_f32_e32 v42, v42
	v_rcp_f32_e32 v43, v43
	v_rcp_f32_e32 v44, v44
	v_rcp_f32_e32 v45, v45
	v_mul_f32_e32 v38, v38, v46
	v_mul_f32_e32 v39, v39, v47
	v_mul_f32_e32 v40, v40, v48
	v_mul_f32_e32 v41, v41, v49
	v_mul_f32_e32 v42, v34, v42
	v_mul_f32_e32 v43, v35, v43
	v_mul_f32_e32 v44, v36, v44
	v_mul_f32_e32 v37, v37, v45
	v_cvt_pkrtz_f16_f32 v34, v38, v39
	v_cvt_pkrtz_f16_f32 v35, v40, v41
	v_cvt_pkrtz_f16_f32 v36, v42, v43
	v_cvt_pkrtz_f16_f32 v37, v44, v37
	global_store_dwordx4 v[52:53], v[34:37], off
	s_nop 1
	v_mov_b32_e32 v34, v197
	v_add_u32_e32 v35, 0xa0, v146
	v_mad_i64_i32 v[36:37], s[8:9], v35, s91, v[114:115]
	v_lshl_add_u64 v[36:37], v[36:37], 0, v[116:117]
	v_pk_mul_f32 v[32:33], v[32:33], v[34:35] op_sel_hi:[1,0]
	v_pk_mul_f32 v[30:31], v[30:31], v[34:35] op_sel_hi:[1,0]
	v_pk_mul_f32 v[28:29], v[28:29], v[34:35] op_sel_hi:[1,0]
	v_pk_mul_f32 v[26:27], v[26:27], v[34:35] op_sel_hi:[1,0]
	v_pk_mul_f32 v[24:25], v[24:25], v[34:35] op_sel_hi:[1,0]
	v_pk_mul_f32 v[22:23], v[22:23], v[34:35] op_sel_hi:[1,0]
	v_pk_mul_f32 v[20:21], v[20:21], v[34:35] op_sel_hi:[1,0]
	v_pk_mul_f32 v[18:19], v[18:19], v[34:35] op_sel_hi:[1,0]
	v_mul_f32_e32 v22, v30, v22
	v_mul_f32_e32 v30, 0xbfb8aa3b, v30
	v_mul_f32_e32 v23, v31, v23
	v_mul_f32_e32 v31, 0xbfb8aa3b, v31
	v_mul_f32_e32 v24, v32, v24
	v_mul_f32_e32 v32, 0xbfb8aa3b, v32
	v_mul_f32_e32 v25, v33, v25
	v_mul_f32_e32 v33, 0xbfb8aa3b, v33
	v_mul_f32_e32 v18, v26, v18
	v_mul_f32_e32 v26, 0xbfb8aa3b, v26
	v_mul_f32_e32 v19, v27, v19
	v_mul_f32_e32 v27, 0xbfb8aa3b, v27
	v_mul_f32_e32 v20, v28, v20
	v_mul_f32_e32 v28, 0xbfb8aa3b, v28
	v_mul_f32_e32 v21, v29, v21
	v_mul_f32_e32 v29, 0xbfb8aa3b, v29
	v_exp_f32_e32 v30, v30
	v_exp_f32_e32 v31, v31
	v_exp_f32_e32 v32, v32
	v_exp_f32_e32 v33, v33
	v_exp_f32_e32 v26, v26
	v_exp_f32_e32 v27, v27
	v_exp_f32_e32 v28, v28
	v_exp_f32_e32 v29, v29
	v_add_f32_e32 v30, 1.0, v30
	v_add_f32_e32 v31, 1.0, v31
	v_add_f32_e32 v32, 1.0, v32
	v_add_f32_e32 v33, 1.0, v33
	v_add_f32_e32 v26, 1.0, v26
	v_add_f32_e32 v27, 1.0, v27
	v_add_f32_e32 v28, 1.0, v28
	v_add_f32_e32 v29, 1.0, v29
	v_rcp_f32_e32 v30, v30
	v_rcp_f32_e32 v31, v31
	v_rcp_f32_e32 v32, v32
	v_rcp_f32_e32 v33, v33
	v_rcp_f32_e32 v26, v26
	v_rcp_f32_e32 v27, v27
	v_rcp_f32_e32 v28, v28
	v_rcp_f32_e32 v29, v29
	v_mul_f32_e32 v22, v22, v30
	v_mul_f32_e32 v23, v23, v31
	v_mul_f32_e32 v24, v24, v32
	v_mul_f32_e32 v25, v25, v33
	v_mul_f32_e32 v26, v18, v26
	v_mul_f32_e32 v27, v19, v27
	v_mul_f32_e32 v28, v20, v28
	v_mul_f32_e32 v21, v21, v29
	v_cvt_pkrtz_f16_f32 v18, v22, v23
	v_cvt_pkrtz_f16_f32 v19, v24, v25
	v_cvt_pkrtz_f16_f32 v20, v26, v27
	v_cvt_pkrtz_f16_f32 v21, v28, v21
	global_store_dwordx4 v[36:37], v[18:21], off
	s_nop 1
	v_mov_b32_e32 v18, v198
	v_add_u32_e32 v19, 0xb0, v146
	v_mad_i64_i32 v[20:21], s[8:9], v19, s91, v[114:115]
	v_lshl_add_u64 v[20:21], v[20:21], 0, v[116:117]
	v_pk_mul_f32 v[16:17], v[16:17], v[18:19] op_sel_hi:[1,0]
	v_pk_mul_f32 v[14:15], v[14:15], v[18:19] op_sel_hi:[1,0]
	v_pk_mul_f32 v[12:13], v[12:13], v[18:19] op_sel_hi:[1,0]
	v_pk_mul_f32 v[10:11], v[10:11], v[18:19] op_sel_hi:[1,0]
	v_pk_mul_f32 v[8:9], v[8:9], v[18:19] op_sel_hi:[1,0]
	v_pk_mul_f32 v[6:7], v[6:7], v[18:19] op_sel_hi:[1,0]
	v_pk_mul_f32 v[4:5], v[4:5], v[18:19] op_sel_hi:[1,0]
	v_pk_mul_f32 v[2:3], v[2:3], v[18:19] op_sel_hi:[1,0]
	v_mul_f32_e32 v6, v14, v6
	v_mul_f32_e32 v14, 0xbfb8aa3b, v14
	v_mul_f32_e32 v7, v15, v7
	v_mul_f32_e32 v15, 0xbfb8aa3b, v15
	v_mul_f32_e32 v8, v16, v8
	v_mul_f32_e32 v16, 0xbfb8aa3b, v16
	v_mul_f32_e32 v9, v17, v9
	v_mul_f32_e32 v17, 0xbfb8aa3b, v17
	v_mul_f32_e32 v2, v10, v2
	v_mul_f32_e32 v10, 0xbfb8aa3b, v10
	v_mul_f32_e32 v3, v11, v3
	v_mul_f32_e32 v11, 0xbfb8aa3b, v11
	v_mul_f32_e32 v4, v12, v4
	v_mul_f32_e32 v12, 0xbfb8aa3b, v12
	v_mul_f32_e32 v5, v13, v5
	v_mul_f32_e32 v13, 0xbfb8aa3b, v13
	v_exp_f32_e32 v14, v14
	v_exp_f32_e32 v15, v15
	v_exp_f32_e32 v16, v16
	v_exp_f32_e32 v17, v17
	v_exp_f32_e32 v10, v10
	v_exp_f32_e32 v11, v11
	v_exp_f32_e32 v12, v12
	v_exp_f32_e32 v13, v13
	v_add_f32_e32 v14, 1.0, v14
	v_add_f32_e32 v15, 1.0, v15
	v_add_f32_e32 v16, 1.0, v16
	v_add_f32_e32 v17, 1.0, v17
	v_add_f32_e32 v10, 1.0, v10
	v_add_f32_e32 v11, 1.0, v11
	v_add_f32_e32 v12, 1.0, v12
	v_add_f32_e32 v13, 1.0, v13
	v_rcp_f32_e32 v14, v14
	v_rcp_f32_e32 v15, v15
	v_rcp_f32_e32 v16, v16
	v_rcp_f32_e32 v17, v17
	v_rcp_f32_e32 v10, v10
	v_rcp_f32_e32 v11, v11
	v_rcp_f32_e32 v12, v12
	v_rcp_f32_e32 v13, v13
	v_mul_f32_e32 v6, v6, v14
	v_mul_f32_e32 v7, v7, v15
	v_mul_f32_e32 v8, v8, v16
	v_mul_f32_e32 v9, v9, v17
	v_mul_f32_e32 v10, v2, v10
	v_mul_f32_e32 v11, v3, v11
	v_mul_f32_e32 v12, v4, v12
	v_mul_f32_e32 v5, v5, v13
	v_cvt_pkrtz_f16_f32 v2, v6, v7
	v_cvt_pkrtz_f16_f32 v3, v8, v9
	v_cvt_pkrtz_f16_f32 v4, v10, v11
	v_cvt_pkrtz_f16_f32 v5, v12, v5
	global_store_dwordx4 v[20:21], v[2:5], off
	s_cbranch_vccnz .LBB0_209
	s_andn2_b64 vcc, exec, s[0:1]
	s_cbranch_vccnz .LBB0_208
	s_barrier
	s_branch .LBB0_208

.LBB0_1018:
	v_lshl_or_b32 v172, s59, 7, v155
	v_ashrrev_i32_e32 v173, 31, v172
	v_lshlrev_b64 v[146:147], 2, v[172:173]
	v_lshl_add_u64 v[152:153], s[6:7], 0, v[146:147]
	v_lshl_add_u64 v[146:147], s[16:17], 0, v[146:147]
	global_load_dwordx4 v[148:151], v[152:153], off
	global_load_dwordx4 v[160:163], v[152:153], off offset:16
	global_load_dwordx4 v[164:167], v[146:147], off
	global_load_dwordx4 v[168:171], v[146:147], off offset:16
	v_lshl_add_u32 v146, s40, 8, v1
	v_ashrrev_i32_e32 v147, 31, v146
	v_lshl_add_u64 v[152:153], v[146:147], 2, s[70:71]
	global_load_dword v174, v[152:153], off
	global_load_dword v192, v[152:153], off offset:64
	global_load_dword v193, v[152:153], off offset:128
	global_load_dword v194, v[152:153], off offset:192
	global_load_dword v195, v[152:153], off offset:512
	global_load_dword v196, v[152:153], off offset:576
	global_load_dword v197, v[152:153], off offset:640
	global_load_dword v198, v[152:153], off offset:704
	v_cvt_f32_i32_e32 v177, v127
	v_cvt_f32_i32_e32 v176, v126
	v_cvt_f32_i32_e32 v185, v119
	v_cvt_f32_i32_e32 v184, v118
	v_cvt_f32_i32_e32 v179, v129
	v_cvt_f32_i32_e32 v178, v128
	v_cvt_f32_i32_e32 v187, v121
	v_cvt_f32_i32_e32 v186, v120
	v_cvt_f32_i32_e32 v189, v115
	v_cvt_f32_i32_e32 v188, v114
	v_mov_b64_e32 v[114:115], s[38:39]
	v_cvt_f32_i32_e32 v191, v117
	v_cvt_f32_i32_e32 v190, v116
	v_mad_i64_i32 v[118:119], s[8:9], v146, s58, v[114:115]
	v_lshlrev_b64 v[116:117], 1, v[172:173]
	v_cvt_f32_i32_e32 v181, v123
	v_cvt_f32_i32_e32 v180, v122
	v_lshl_add_u64 v[172:173], v[118:119], 0, v[116:117]
	v_cvt_f32_i32_e32 v183, v125
	v_cvt_f32_i32_e32 v182, v124
	v_cvt_f32_i32_e32 v111, v111
	v_cvt_f32_i32_e32 v110, v110
	v_cvt_f32_i32_e32 v103, v103
	v_cvt_f32_i32_e32 v102, v102
	v_cvt_f32_i32_e32 v113, v113
	v_cvt_f32_i32_e32 v112, v112
	v_cvt_f32_i32_e32 v107, v107
	v_cvt_f32_i32_e32 v106, v106
	v_cvt_f32_i32_e32 v99, v99
	v_cvt_f32_i32_e32 v98, v98
	v_cvt_f32_i32_e32 v101, v101
	v_cvt_f32_i32_e32 v100, v100
	v_cvt_f32_i32_e32 v109, v109
	v_cvt_f32_i32_e32 v108, v108
	v_cvt_f32_i32_e32 v105, v105
	v_cvt_f32_i32_e32 v104, v104
	v_cvt_f32_i32_e32 v95, v95
	v_cvt_f32_i32_e32 v94, v94
	v_cvt_f32_i32_e32 v87, v87
	v_cvt_f32_i32_e32 v86, v86
	v_cvt_f32_i32_e32 v97, v97
	v_cvt_f32_i32_e32 v96, v96
	v_cvt_f32_i32_e32 v91, v91
	v_cvt_f32_i32_e32 v90, v90
	v_cvt_f32_i32_e32 v83, v83
	v_cvt_f32_i32_e32 v82, v82
	v_cvt_f32_i32_e32 v85, v85
	v_cvt_f32_i32_e32 v84, v84
	v_cvt_f32_i32_e32 v93, v93
	v_cvt_f32_i32_e32 v92, v92
	v_cvt_f32_i32_e32 v89, v89
	v_cvt_f32_i32_e32 v88, v88
	v_cvt_f32_i32_e32 v79, v79
	v_cvt_f32_i32_e32 v78, v78
	v_cvt_f32_i32_e32 v81, v81
	v_cvt_f32_i32_e32 v80, v80
	v_cvt_f32_i32_e32 v71, v71
	v_cvt_f32_i32_e32 v70, v70
	v_cvt_f32_i32_e32 v75, v75
	v_cvt_f32_i32_e32 v74, v74
	v_cvt_f32_i32_e32 v67, v67
	v_cvt_f32_i32_e32 v66, v66
	v_cvt_f32_i32_e32 v69, v69
	v_cvt_f32_i32_e32 v68, v68
	v_cvt_f32_i32_e32 v77, v77
	v_cvt_f32_i32_e32 v76, v76
	v_cvt_f32_i32_e32 v73, v73
	v_cvt_f32_i32_e32 v72, v72
	v_cvt_f32_i32_e32 v63, v63
	v_cvt_f32_i32_e32 v62, v62
	v_cvt_f32_i32_e32 v65, v65
	v_cvt_f32_i32_e32 v64, v64
	s_waitcnt vmcnt(0)
	v_pk_mul_f32 v[120:121], v[148:149], s[18:19] op_sel_hi:[1,0]
	v_pk_mul_f32 v[128:129], v[164:165], s[18:19] op_sel_hi:[1,0]
	v_pk_mul_f32 v[118:119], v[150:151], s[18:19] op_sel_hi:[1,0]
	v_pk_mul_f32 v[122:123], v[162:163], s[18:19] op_sel_hi:[1,0]
	v_pk_mul_f32 v[126:127], v[166:167], s[18:19] op_sel_hi:[1,0]
	v_pk_mul_f32 v[148:149], v[170:171], s[18:19] op_sel_hi:[1,0]
	v_pk_mul_f32 v[162:163], v[120:121], v[176:177]
	v_pk_mul_f32 v[170:171], v[128:129], v[184:185]
	v_pk_mul_f32 v[124:125], v[160:161], s[18:19] op_sel_hi:[1,0]
	v_pk_mul_f32 v[150:151], v[168:169], s[18:19] op_sel_hi:[1,0]
	v_pk_mul_f32 v[160:161], v[118:119], v[178:179]
	v_pk_mul_f32 v[168:169], v[126:127], v[186:187]
	v_pk_mul_f32 v[162:163], v[162:163], v[174:175] op_sel_hi:[1,0]
	v_pk_mul_f32 v[170:171], v[170:171], v[174:175] op_sel_hi:[1,0]
	v_pk_mul_f32 v[160:161], v[160:161], v[174:175] op_sel_hi:[1,0]
	v_pk_mul_f32 v[168:169], v[168:169], v[174:175] op_sel_hi:[1,0]
	v_mul_f32_e32 v147, v162, v170
	v_mul_f32_e32 v159, 0xbfb8aa3b, v162
	v_mul_f32_e32 v162, v163, v171
	v_mul_f32_e32 v163, 0xbfb8aa3b, v163
	v_mul_f32_e32 v168, v160, v168
	v_mul_f32_e32 v160, 0xbfb8aa3b, v160
	v_exp_f32_e32 v159, v159
	v_exp_f32_e32 v163, v163
	v_exp_f32_e32 v160, v160
	v_pk_mul_f32 v[164:165], v[122:123], v[182:183]
	v_pk_mul_f32 v[166:167], v[124:125], v[180:181]
	v_pk_mul_f32 v[176:177], v[148:149], v[190:191]
	v_pk_mul_f32 v[178:179], v[150:151], v[188:189]
	v_add_f32_e32 v159, 1.0, v159
	v_add_f32_e32 v163, 1.0, v163
	v_pk_mul_f32 v[164:165], v[164:165], v[174:175] op_sel_hi:[1,0]
	v_pk_mul_f32 v[166:167], v[166:167], v[174:175] op_sel_hi:[1,0]
	v_pk_mul_f32 v[176:177], v[176:177], v[174:175] op_sel_hi:[1,0]
	v_pk_mul_f32 v[174:175], v[178:179], v[174:175] op_sel_hi:[1,0]
	v_add_f32_e32 v160, 1.0, v160
	v_rcp_f32_e32 v159, v159
	v_rcp_f32_e32 v163, v163
	v_mul_f32_e32 v169, v161, v169
	v_mul_f32_e32 v161, 0xbfb8aa3b, v161
	v_mul_f32_e32 v170, v166, v174
	v_mul_f32_e32 v166, 0xbfb8aa3b, v166
	v_mul_f32_e32 v171, v167, v175
	v_mul_f32_e32 v167, 0xbfb8aa3b, v167
	v_rcp_f32_e32 v160, v160
	v_exp_f32_e32 v161, v161
	v_exp_f32_e32 v166, v166
	v_exp_f32_e32 v167, v167
	v_mul_f32_e32 v174, 0xbfb8aa3b, v164
	v_mul_f32_e32 v175, 0xbfb8aa3b, v165
	v_exp_f32_e32 v174, v174
	v_mul_f32_e32 v147, v147, v159
	v_mul_f32_e32 v159, v162, v163
	v_mul_f32_e32 v162, v168, v160
	v_cvt_pkrtz_f16_f32 v160, v147, v159
	v_exp_f32_e32 v147, v175
	v_add_f32_e32 v161, 1.0, v161
	v_add_f32_e32 v166, 1.0, v166
	v_add_f32_e32 v167, 1.0, v167
	v_rcp_f32_e32 v161, v161
	v_rcp_f32_e32 v166, v166
	v_rcp_f32_e32 v167, v167
	v_add_f32_e32 v159, 1.0, v174
	v_rcp_f32_e32 v159, v159
	v_add_f32_e32 v147, 1.0, v147
	v_rcp_f32_e32 v147, v147
	v_mul_f32_e32 v161, v169, v161
	v_mul_f32_e32 v163, v170, v166
	v_mul_f32_e32 v166, v171, v167
	v_cvt_pkrtz_f16_f32 v161, v162, v161
	v_cvt_pkrtz_f16_f32 v162, v163, v166
	v_mul_f32_e32 v163, v164, v176
	v_mul_f32_e32 v159, v163, v159
	v_mul_f32_e32 v163, v165, v177
	v_mul_f32_e32 v147, v163, v147
	v_cvt_pkrtz_f16_f32 v163, v159, v147
	global_store_dwordx4 v[172:173], v[160:163], off
	v_pk_mul_f32 v[110:111], v[120:121], v[110:111]
	v_pk_mul_f32 v[102:103], v[128:129], v[102:103]
	v_or_b32_e32 v160, 16, v146
	v_ashrrev_i32_e32 v161, 31, v160
	v_lshl_add_u64 v[162:163], v[160:161], 2, s[70:71]
	v_mov_b32_e32 v162, v192
	v_pk_mul_f32 v[112:113], v[118:119], v[112:113]
	v_pk_mul_f32 v[106:107], v[124:125], v[106:107]
	v_pk_mul_f32 v[100:101], v[148:149], v[100:101]
	v_pk_mul_f32 v[98:99], v[150:151], v[98:99]
	v_pk_mul_f32 v[108:109], v[122:123], v[108:109]
	v_pk_mul_f32 v[104:105], v[126:127], v[104:105]
	v_mad_i64_i32 v[160:161], s[8:9], v160, s58, v[114:115]
	v_lshl_add_u64 v[160:161], v[160:161], 0, v[116:117]
	v_pk_mul_f32 v[94:95], v[120:121], v[94:95]
	v_pk_mul_f32 v[86:87], v[128:129], v[86:87]
	v_pk_mul_f32 v[96:97], v[118:119], v[96:97]
	v_pk_mul_f32 v[90:91], v[124:125], v[90:91]
	v_pk_mul_f32 v[84:85], v[148:149], v[84:85]
	v_pk_mul_f32 v[82:83], v[150:151], v[82:83]
	v_pk_mul_f32 v[92:93], v[122:123], v[92:93]
	v_pk_mul_f32 v[88:89], v[126:127], v[88:89]
	v_pk_mul_f32 v[80:81], v[118:119], v[80:81]
	v_pk_mul_f32 v[78:79], v[120:121], v[78:79]
	v_pk_mul_f32 v[70:71], v[128:129], v[70:71]
	v_pk_mul_f32 v[74:75], v[124:125], v[74:75]
	v_pk_mul_f32 v[68:69], v[148:149], v[68:69]
	v_pk_mul_f32 v[66:67], v[150:151], v[66:67]
	v_pk_mul_f32 v[76:77], v[122:123], v[76:77]
	v_pk_mul_f32 v[72:73], v[126:127], v[72:73]
	v_cvt_f32_i32_e32 v59, v59
	v_cvt_f32_i32_e32 v58, v58
	v_cvt_f32_i32_e32 v61, v61
	v_cvt_f32_i32_e32 v60, v60
	v_cvt_f32_i32_e32 v55, v55
	v_cvt_f32_i32_e32 v54, v54
	v_cvt_f32_i32_e32 v57, v57
	v_cvt_f32_i32_e32 v56, v56
	v_cvt_f32_i32_e32 v51, v51
	v_cvt_f32_i32_e32 v50, v50
	v_cvt_f32_i32_e32 v53, v53
	v_cvt_f32_i32_e32 v52, v52
	v_pk_mul_f32 v[64:65], v[118:119], v[64:65]
	v_pk_mul_f32 v[62:63], v[120:121], v[62:63]
	v_pk_mul_f32 v[60:61], v[122:123], v[60:61]
	v_pk_mul_f32 v[58:59], v[124:125], v[58:59]
	v_pk_mul_f32 v[56:57], v[126:127], v[56:57]
	v_pk_mul_f32 v[54:55], v[128:129], v[54:55]
	v_pk_mul_f32 v[52:53], v[148:149], v[52:53]
	v_pk_mul_f32 v[50:51], v[150:151], v[50:51]
	v_cvt_f32_i32_e32 v47, v47
	v_cvt_f32_i32_e32 v46, v46
	v_cvt_f32_i32_e32 v49, v49
	v_cvt_f32_i32_e32 v48, v48
	v_cvt_f32_i32_e32 v43, v43
	v_cvt_f32_i32_e32 v42, v42
	v_cvt_f32_i32_e32 v45, v45
	v_cvt_f32_i32_e32 v44, v44
	v_cvt_f32_i32_e32 v39, v39
	v_cvt_f32_i32_e32 v38, v38
	v_cvt_f32_i32_e32 v41, v41
	v_cvt_f32_i32_e32 v40, v40
	v_cvt_f32_i32_e32 v35, v35
	v_cvt_f32_i32_e32 v34, v34
	v_cvt_f32_i32_e32 v37, v37
	v_cvt_f32_i32_e32 v36, v36
	v_pk_mul_f32 v[48:49], v[118:119], v[48:49]
	v_pk_mul_f32 v[46:47], v[120:121], v[46:47]
	v_pk_mul_f32 v[44:45], v[122:123], v[44:45]
	v_pk_mul_f32 v[42:43], v[124:125], v[42:43]
	v_pk_mul_f32 v[40:41], v[126:127], v[40:41]
	v_pk_mul_f32 v[38:39], v[128:129], v[38:39]
	v_pk_mul_f32 v[36:37], v[148:149], v[36:37]
	v_pk_mul_f32 v[34:35], v[150:151], v[34:35]
	v_cvt_f32_i32_e32 v31, v31
	v_cvt_f32_i32_e32 v30, v30
	v_cvt_f32_i32_e32 v33, v33
	v_cvt_f32_i32_e32 v32, v32
	v_cvt_f32_i32_e32 v27, v27
	v_cvt_f32_i32_e32 v26, v26
	v_cvt_f32_i32_e32 v29, v29
	v_cvt_f32_i32_e32 v28, v28
	v_cvt_f32_i32_e32 v23, v23
	v_cvt_f32_i32_e32 v22, v22
	v_pk_mul_f32 v[110:111], v[110:111], v[162:163] op_sel_hi:[1,0]
	v_pk_mul_f32 v[102:103], v[102:103], v[162:163] op_sel_hi:[1,0]
	v_pk_mul_f32 v[112:113], v[112:113], v[162:163] op_sel_hi:[1,0]
	v_pk_mul_f32 v[106:107], v[106:107], v[162:163] op_sel_hi:[1,0]
	v_pk_mul_f32 v[164:165], v[100:101], v[162:163] op_sel_hi:[1,0]
	v_pk_mul_f32 v[98:99], v[98:99], v[162:163] op_sel_hi:[1,0]
	v_mul_f32_e32 v100, v110, v102
	v_mul_f32_e32 v101, 0xbfb8aa3b, v110
	v_mul_f32_e32 v102, v111, v103
	v_mul_f32_e32 v103, 0xbfb8aa3b, v111
	v_mul_f32_e32 v110, 0xbfb8aa3b, v112
	v_mul_f32_e32 v111, 0xbfb8aa3b, v113
	v_mul_f32_e32 v98, v106, v98
	v_mul_f32_e32 v106, 0xbfb8aa3b, v106
	v_exp_f32_e32 v101, v101
	v_exp_f32_e32 v103, v103
	v_mul_f32_e32 v99, v107, v99
	v_mul_f32_e32 v107, 0xbfb8aa3b, v107
	v_exp_f32_e32 v110, v110
	v_exp_f32_e32 v111, v111
	v_exp_f32_e32 v106, v106
	v_exp_f32_e32 v107, v107
	v_pk_mul_f32 v[108:109], v[108:109], v[162:163] op_sel_hi:[1,0]
	v_pk_mul_f32 v[104:105], v[104:105], v[162:163] op_sel_hi:[1,0]
	v_add_f32_e32 v101, 1.0, v101
	v_add_f32_e32 v103, 1.0, v103
	v_mul_f32_e32 v104, v112, v104
	v_mul_f32_e32 v112, 0xbfb8aa3b, v108
	v_add_f32_e32 v110, 1.0, v110
	v_add_f32_e32 v111, 1.0, v111
	v_add_f32_e32 v106, 1.0, v106
	v_rcp_f32_e32 v101, v101
	v_rcp_f32_e32 v103, v103
	v_mul_f32_e32 v105, v113, v105
	v_mul_f32_e32 v113, 0xbfb8aa3b, v109
	v_exp_f32_e32 v112, v112
	v_add_f32_e32 v107, 1.0, v107
	v_rcp_f32_e32 v110, v110
	v_rcp_f32_e32 v111, v111
	v_rcp_f32_e32 v106, v106
	v_exp_f32_e32 v113, v113
	v_rcp_f32_e32 v107, v107
	v_mul_f32_e32 v100, v100, v101
	v_mul_f32_e32 v101, v102, v103
	v_mul_f32_e32 v102, v104, v110
	v_mul_f32_e32 v103, v105, v111
	v_mul_f32_e32 v104, v98, v106
	v_cvt_pkrtz_f16_f32 v98, v100, v101
	v_add_f32_e32 v101, 1.0, v112
	v_mul_f32_e32 v105, v99, v107
	v_cvt_pkrtz_f16_f32 v99, v102, v103
	v_rcp_f32_e32 v101, v101
	v_add_f32_e32 v102, 1.0, v113
	v_rcp_f32_e32 v102, v102
	v_mul_f32_e32 v103, v108, v164
	v_mul_f32_e32 v101, v103, v101
	v_mul_f32_e32 v103, v109, v165
	v_mul_f32_e32 v102, v103, v102
	v_cvt_pkrtz_f16_f32 v100, v104, v105
	v_cvt_pkrtz_f16_f32 v101, v101, v102
	global_store_dwordx4 v[160:161], v[98:101], off
	v_cvt_f32_i32_e32 v25, v25
	v_cvt_f32_i32_e32 v24, v24
	v_or_b32_e32 v98, 32, v146
	v_ashrrev_i32_e32 v99, 31, v98
	v_lshl_add_u64 v[100:101], v[98:99], 2, s[70:71]
	v_mov_b32_e32 v100, v193
	v_mad_i64_i32 v[98:99], s[8:9], v98, s58, v[114:115]
	v_lshl_add_u64 v[98:99], v[98:99], 0, v[116:117]
	v_cvt_f32_i32_e32 v19, v19
	v_cvt_f32_i32_e32 v18, v18
	v_cvt_f32_i32_e32 v21, v21
	v_cvt_f32_i32_e32 v20, v20
	v_pk_mul_f32 v[32:33], v[118:119], v[32:33]
	v_pk_mul_f32 v[30:31], v[120:121], v[30:31]
	v_pk_mul_f32 v[28:29], v[122:123], v[28:29]
	v_pk_mul_f32 v[26:27], v[124:125], v[26:27]
	v_pk_mul_f32 v[24:25], v[126:127], v[24:25]
	v_pk_mul_f32 v[22:23], v[128:129], v[22:23]
	v_pk_mul_f32 v[20:21], v[148:149], v[20:21]
	v_pk_mul_f32 v[18:19], v[150:151], v[18:19]
	v_cvt_f32_i32_e32 v15, v15
	v_cvt_f32_i32_e32 v14, v14
	v_cvt_f32_i32_e32 v17, v17
	v_cvt_f32_i32_e32 v16, v16
	v_cvt_f32_i32_e32 v11, v11
	v_cvt_f32_i32_e32 v10, v10
	v_cvt_f32_i32_e32 v13, v13
	v_cvt_f32_i32_e32 v12, v12
	v_cvt_f32_i32_e32 v7, v7
	v_cvt_f32_i32_e32 v6, v6
	v_cvt_f32_i32_e32 v9, v9
	v_cvt_f32_i32_e32 v8, v8
	v_cvt_f32_i32_e32 v3, v3
	v_cvt_f32_i32_e32 v2, v2
	v_cvt_f32_i32_e32 v5, v5
	v_cvt_f32_i32_e32 v4, v4
	v_pk_mul_f32 v[16:17], v[118:119], v[16:17]
	v_pk_mul_f32 v[14:15], v[120:121], v[14:15]
	v_pk_mul_f32 v[12:13], v[122:123], v[12:13]
	v_pk_mul_f32 v[10:11], v[124:125], v[10:11]
	v_pk_mul_f32 v[8:9], v[126:127], v[8:9]
	v_pk_mul_f32 v[6:7], v[128:129], v[6:7]
	v_pk_mul_f32 v[4:5], v[148:149], v[4:5]
	v_pk_mul_f32 v[2:3], v[150:151], v[2:3]
	s_andn2_b64 vcc, exec, s[2:3]
	s_mov_b64 s[2:3], -1
	v_pk_mul_f32 v[94:95], v[94:95], v[100:101] op_sel_hi:[1,0]
	v_pk_mul_f32 v[86:87], v[86:87], v[100:101] op_sel_hi:[1,0]
	v_pk_mul_f32 v[96:97], v[96:97], v[100:101] op_sel_hi:[1,0]
	v_pk_mul_f32 v[90:91], v[90:91], v[100:101] op_sel_hi:[1,0]
	v_pk_mul_f32 v[102:103], v[84:85], v[100:101] op_sel_hi:[1,0]
	v_pk_mul_f32 v[82:83], v[82:83], v[100:101] op_sel_hi:[1,0]
	v_mul_f32_e32 v84, v94, v86
	v_mul_f32_e32 v85, 0xbfb8aa3b, v94
	v_mul_f32_e32 v86, v95, v87
	v_mul_f32_e32 v87, 0xbfb8aa3b, v95
	v_mul_f32_e32 v94, 0xbfb8aa3b, v96
	v_mul_f32_e32 v82, v90, v82
	v_mul_f32_e32 v90, 0xbfb8aa3b, v90
	v_exp_f32_e32 v85, v85
	v_exp_f32_e32 v87, v87
	v_exp_f32_e32 v94, v94
	v_exp_f32_e32 v90, v90
	v_mul_f32_e32 v95, 0xbfb8aa3b, v97
	v_pk_mul_f32 v[92:93], v[92:93], v[100:101] op_sel_hi:[1,0]
	v_pk_mul_f32 v[88:89], v[88:89], v[100:101] op_sel_hi:[1,0]
	v_mul_f32_e32 v83, v91, v83
	v_mul_f32_e32 v91, 0xbfb8aa3b, v91
	v_exp_f32_e32 v95, v95
	v_add_f32_e32 v85, 1.0, v85
	v_add_f32_e32 v87, 1.0, v87
	v_mul_f32_e32 v88, v96, v88
	v_mul_f32_e32 v89, v97, v89
	v_mul_f32_e32 v96, 0xbfb8aa3b, v92
	v_mul_f32_e32 v97, 0xbfb8aa3b, v93
	v_exp_f32_e32 v91, v91
	v_add_f32_e32 v94, 1.0, v94
	v_add_f32_e32 v90, 1.0, v90
	v_rcp_f32_e32 v85, v85
	v_rcp_f32_e32 v87, v87
	v_exp_f32_e32 v96, v96
	v_exp_f32_e32 v97, v97
	v_rcp_f32_e32 v94, v94
	v_rcp_f32_e32 v90, v90
	v_add_f32_e32 v95, 1.0, v95
	v_add_f32_e32 v91, 1.0, v91
	v_rcp_f32_e32 v95, v95
	v_mul_f32_e32 v84, v84, v85
	v_mul_f32_e32 v85, v86, v87
	v_add_f32_e32 v96, 1.0, v96
	v_rcp_f32_e32 v91, v91
	v_mul_f32_e32 v86, v88, v94
	v_mul_f32_e32 v88, v82, v90
	v_cvt_pkrtz_f16_f32 v82, v84, v85
	v_add_f32_e32 v85, 1.0, v97
	v_rcp_f32_e32 v96, v96
	v_rcp_f32_e32 v85, v85
	v_mul_f32_e32 v87, v89, v95
	v_mul_f32_e32 v89, v83, v91
	v_cvt_pkrtz_f16_f32 v83, v86, v87
	v_mul_f32_e32 v86, v92, v102
	v_mul_f32_e32 v87, v93, v103
	v_mul_f32_e32 v86, v86, v96
	v_mul_f32_e32 v85, v87, v85
	v_cvt_pkrtz_f16_f32 v84, v88, v89
	v_cvt_pkrtz_f16_f32 v85, v86, v85
	global_store_dwordx4 v[98:99], v[82:85], off
	s_nop 1
	v_or_b32_e32 v82, 48, v146
	v_ashrrev_i32_e32 v83, 31, v82
	v_lshl_add_u64 v[84:85], v[82:83], 2, s[70:71]
	v_mov_b32_e32 v84, v194
	v_mad_i64_i32 v[82:83], s[8:9], v82, s58, v[114:115]
	v_lshl_add_u64 v[82:83], v[82:83], 0, v[116:117]
	v_pk_mul_f32 v[80:81], v[80:81], v[84:85] op_sel_hi:[1,0]
	v_pk_mul_f32 v[78:79], v[78:79], v[84:85] op_sel_hi:[1,0]
	v_pk_mul_f32 v[70:71], v[70:71], v[84:85] op_sel_hi:[1,0]
	v_pk_mul_f32 v[74:75], v[74:75], v[84:85] op_sel_hi:[1,0]
	v_pk_mul_f32 v[86:87], v[68:69], v[84:85] op_sel_hi:[1,0]
	v_pk_mul_f32 v[66:67], v[66:67], v[84:85] op_sel_hi:[1,0]
	v_mul_f32_e32 v68, v78, v70
	v_mul_f32_e32 v69, 0xbfb8aa3b, v78
	v_mul_f32_e32 v70, v79, v71
	v_mul_f32_e32 v71, 0xbfb8aa3b, v79
	v_mul_f32_e32 v78, 0xbfb8aa3b, v80
	v_mul_f32_e32 v79, 0xbfb8aa3b, v81
	v_pk_mul_f32 v[76:77], v[76:77], v[84:85] op_sel_hi:[1,0]
	v_pk_mul_f32 v[72:73], v[72:73], v[84:85] op_sel_hi:[1,0]
	v_mul_f32_e32 v66, v74, v66
	v_mul_f32_e32 v74, 0xbfb8aa3b, v74
	v_mul_f32_e32 v67, v75, v67
	v_mul_f32_e32 v75, 0xbfb8aa3b, v75
	v_exp_f32_e32 v69, v69
	v_exp_f32_e32 v71, v71
	v_exp_f32_e32 v78, v78
	v_exp_f32_e32 v79, v79
	v_mul_f32_e32 v72, v80, v72
	v_mul_f32_e32 v73, v81, v73
	v_mul_f32_e32 v80, 0xbfb8aa3b, v76
	v_mul_f32_e32 v81, 0xbfb8aa3b, v77
	v_exp_f32_e32 v74, v74
	v_exp_f32_e32 v75, v75
	v_exp_f32_e32 v80, v80
	v_exp_f32_e32 v81, v81
	v_add_f32_e32 v69, 1.0, v69
	v_add_f32_e32 v71, 1.0, v71
	v_add_f32_e32 v78, 1.0, v78
	v_add_f32_e32 v79, 1.0, v79
	v_add_f32_e32 v74, 1.0, v74
	v_add_f32_e32 v75, 1.0, v75
	v_rcp_f32_e32 v69, v69
	v_rcp_f32_e32 v71, v71
	v_rcp_f32_e32 v78, v78
	v_rcp_f32_e32 v79, v79
	v_add_f32_e32 v80, 1.0, v80
	v_add_f32_e32 v81, 1.0, v81
	v_rcp_f32_e32 v74, v74
	v_rcp_f32_e32 v75, v75
	v_rcp_f32_e32 v80, v80
	v_rcp_f32_e32 v81, v81
	v_mul_f32_e32 v68, v68, v69
	v_mul_f32_e32 v69, v70, v71
	v_mul_f32_e32 v70, v72, v78
	v_mul_f32_e32 v71, v73, v79
	v_mul_f32_e32 v72, v66, v74
	v_mul_f32_e32 v73, v67, v75
	v_cvt_pkrtz_f16_f32 v66, v68, v69
	v_cvt_pkrtz_f16_f32 v67, v70, v71
	v_mul_f32_e32 v69, v76, v86
	v_mul_f32_e32 v70, v77, v87
	v_mul_f32_e32 v69, v69, v80
	v_mul_f32_e32 v70, v70, v81
	v_cvt_pkrtz_f16_f32 v68, v72, v73
	v_cvt_pkrtz_f16_f32 v69, v69, v70
	global_store_dwordx4 v[82:83], v[66:69], off
	s_nop 1
	v_mov_b32_e32 v66, v195
	v_add_u32_e32 v67, 0x80, v146
	v_mad_i64_i32 v[68:69], s[8:9], v67, s58, v[114:115]
	v_lshl_add_u64 v[68:69], v[68:69], 0, v[116:117]
	v_pk_mul_f32 v[64:65], v[64:65], v[66:67] op_sel_hi:[1,0]
	v_pk_mul_f32 v[62:63], v[62:63], v[66:67] op_sel_hi:[1,0]
	v_pk_mul_f32 v[60:61], v[60:61], v[66:67] op_sel_hi:[1,0]
	v_pk_mul_f32 v[58:59], v[58:59], v[66:67] op_sel_hi:[1,0]
	v_pk_mul_f32 v[56:57], v[56:57], v[66:67] op_sel_hi:[1,0]
	v_pk_mul_f32 v[54:55], v[54:55], v[66:67] op_sel_hi:[1,0]
	v_pk_mul_f32 v[52:53], v[52:53], v[66:67] op_sel_hi:[1,0]
	v_pk_mul_f32 v[50:51], v[50:51], v[66:67] op_sel_hi:[1,0]
	v_mul_f32_e32 v54, v62, v54
	v_mul_f32_e32 v62, 0xbfb8aa3b, v62
	v_mul_f32_e32 v55, v63, v55
	v_mul_f32_e32 v63, 0xbfb8aa3b, v63
	v_mul_f32_e32 v56, v64, v56
	v_mul_f32_e32 v64, 0xbfb8aa3b, v64
	v_mul_f32_e32 v57, v65, v57
	v_mul_f32_e32 v65, 0xbfb8aa3b, v65
	v_mul_f32_e32 v50, v58, v50
	v_mul_f32_e32 v58, 0xbfb8aa3b, v58
	v_mul_f32_e32 v51, v59, v51
	v_mul_f32_e32 v59, 0xbfb8aa3b, v59
	v_mul_f32_e32 v52, v60, v52
	v_mul_f32_e32 v60, 0xbfb8aa3b, v60
	v_mul_f32_e32 v53, v61, v53
	v_mul_f32_e32 v61, 0xbfb8aa3b, v61
	v_exp_f32_e32 v62, v62
	v_exp_f32_e32 v63, v63
	v_exp_f32_e32 v64, v64
	v_exp_f32_e32 v65, v65
	v_exp_f32_e32 v58, v58
	v_exp_f32_e32 v59, v59
	v_exp_f32_e32 v60, v60
	v_exp_f32_e32 v61, v61
	v_add_f32_e32 v62, 1.0, v62
	v_add_f32_e32 v63, 1.0, v63
	v_add_f32_e32 v64, 1.0, v64
	v_add_f32_e32 v65, 1.0, v65
	v_add_f32_e32 v58, 1.0, v58
	v_add_f32_e32 v59, 1.0, v59
	v_add_f32_e32 v60, 1.0, v60
	v_add_f32_e32 v61, 1.0, v61
	v_rcp_f32_e32 v62, v62
	v_rcp_f32_e32 v63, v63
	v_rcp_f32_e32 v64, v64
	v_rcp_f32_e32 v65, v65
	v_rcp_f32_e32 v58, v58
	v_rcp_f32_e32 v59, v59
	v_rcp_f32_e32 v60, v60
	v_rcp_f32_e32 v61, v61
	v_mul_f32_e32 v54, v54, v62
	v_mul_f32_e32 v55, v55, v63
	v_mul_f32_e32 v56, v56, v64
	v_mul_f32_e32 v57, v57, v65
	v_mul_f32_e32 v58, v50, v58
	v_mul_f32_e32 v59, v51, v59
	v_mul_f32_e32 v60, v52, v60
	v_mul_f32_e32 v53, v53, v61
	v_cvt_pkrtz_f16_f32 v50, v54, v55
	v_cvt_pkrtz_f16_f32 v51, v56, v57
	v_cvt_pkrtz_f16_f32 v52, v58, v59
	v_cvt_pkrtz_f16_f32 v53, v60, v53
	global_store_dwordx4 v[68:69], v[50:53], off
	s_nop 1
	v_mov_b32_e32 v50, v196
	v_add_u32_e32 v51, 0x90, v146
	v_mad_i64_i32 v[52:53], s[8:9], v51, s58, v[114:115]
	v_lshl_add_u64 v[52:53], v[52:53], 0, v[116:117]
	v_pk_mul_f32 v[48:49], v[48:49], v[50:51] op_sel_hi:[1,0]
	v_pk_mul_f32 v[46:47], v[46:47], v[50:51] op_sel_hi:[1,0]
	v_pk_mul_f32 v[44:45], v[44:45], v[50:51] op_sel_hi:[1,0]
	v_pk_mul_f32 v[42:43], v[42:43], v[50:51] op_sel_hi:[1,0]
	v_pk_mul_f32 v[40:41], v[40:41], v[50:51] op_sel_hi:[1,0]
	v_pk_mul_f32 v[38:39], v[38:39], v[50:51] op_sel_hi:[1,0]
	v_pk_mul_f32 v[36:37], v[36:37], v[50:51] op_sel_hi:[1,0]
	v_pk_mul_f32 v[34:35], v[34:35], v[50:51] op_sel_hi:[1,0]
	v_mul_f32_e32 v38, v46, v38
	v_mul_f32_e32 v46, 0xbfb8aa3b, v46
	v_mul_f32_e32 v39, v47, v39
	v_mul_f32_e32 v47, 0xbfb8aa3b, v47
	v_mul_f32_e32 v40, v48, v40
	v_mul_f32_e32 v48, 0xbfb8aa3b, v48
	v_mul_f32_e32 v41, v49, v41
	v_mul_f32_e32 v49, 0xbfb8aa3b, v49
	v_mul_f32_e32 v34, v42, v34
	v_mul_f32_e32 v42, 0xbfb8aa3b, v42
	v_mul_f32_e32 v35, v43, v35
	v_mul_f32_e32 v43, 0xbfb8aa3b, v43
	v_mul_f32_e32 v36, v44, v36
	v_mul_f32_e32 v44, 0xbfb8aa3b, v44
	v_mul_f32_e32 v37, v45, v37
	v_mul_f32_e32 v45, 0xbfb8aa3b, v45
	v_exp_f32_e32 v46, v46
	v_exp_f32_e32 v47, v47
	v_exp_f32_e32 v48, v48
	v_exp_f32_e32 v49, v49
	v_exp_f32_e32 v42, v42
	v_exp_f32_e32 v43, v43
	v_exp_f32_e32 v44, v44
	v_exp_f32_e32 v45, v45
	v_add_f32_e32 v46, 1.0, v46
	v_add_f32_e32 v47, 1.0, v47
	v_add_f32_e32 v48, 1.0, v48
	v_add_f32_e32 v49, 1.0, v49
	v_add_f32_e32 v42, 1.0, v42
	v_add_f32_e32 v43, 1.0, v43
	v_add_f32_e32 v44, 1.0, v44
	v_add_f32_e32 v45, 1.0, v45
	v_rcp_f32_e32 v46, v46
	v_rcp_f32_e32 v47, v47
	v_rcp_f32_e32 v48, v48
	v_rcp_f32_e32 v49, v49
	v_rcp_f32_e32 v42, v42
	v_rcp_f32_e32 v43, v43
	v_rcp_f32_e32 v44, v44
	v_rcp_f32_e32 v45, v45
	v_mul_f32_e32 v38, v38, v46
	v_mul_f32_e32 v39, v39, v47
	v_mul_f32_e32 v40, v40, v48
	v_mul_f32_e32 v41, v41, v49
	v_mul_f32_e32 v42, v34, v42
	v_mul_f32_e32 v43, v35, v43
	v_mul_f32_e32 v44, v36, v44
	v_mul_f32_e32 v37, v37, v45
	v_cvt_pkrtz_f16_f32 v34, v38, v39
	v_cvt_pkrtz_f16_f32 v35, v40, v41
	v_cvt_pkrtz_f16_f32 v36, v42, v43
	v_cvt_pkrtz_f16_f32 v37, v44, v37
	global_store_dwordx4 v[52:53], v[34:37], off
	s_nop 1
	v_mov_b32_e32 v34, v197
	v_add_u32_e32 v35, 0xa0, v146
	v_mad_i64_i32 v[36:37], s[8:9], v35, s58, v[114:115]
	v_lshl_add_u64 v[36:37], v[36:37], 0, v[116:117]
	v_pk_mul_f32 v[32:33], v[32:33], v[34:35] op_sel_hi:[1,0]
	v_pk_mul_f32 v[30:31], v[30:31], v[34:35] op_sel_hi:[1,0]
	v_pk_mul_f32 v[28:29], v[28:29], v[34:35] op_sel_hi:[1,0]
	v_pk_mul_f32 v[26:27], v[26:27], v[34:35] op_sel_hi:[1,0]
	v_pk_mul_f32 v[24:25], v[24:25], v[34:35] op_sel_hi:[1,0]
	v_pk_mul_f32 v[22:23], v[22:23], v[34:35] op_sel_hi:[1,0]
	v_pk_mul_f32 v[20:21], v[20:21], v[34:35] op_sel_hi:[1,0]
	v_pk_mul_f32 v[18:19], v[18:19], v[34:35] op_sel_hi:[1,0]
	v_mul_f32_e32 v22, v30, v22
	v_mul_f32_e32 v30, 0xbfb8aa3b, v30
	v_mul_f32_e32 v23, v31, v23
	v_mul_f32_e32 v31, 0xbfb8aa3b, v31
	v_mul_f32_e32 v24, v32, v24
	v_mul_f32_e32 v32, 0xbfb8aa3b, v32
	v_mul_f32_e32 v25, v33, v25
	v_mul_f32_e32 v33, 0xbfb8aa3b, v33
	v_mul_f32_e32 v18, v26, v18
	v_mul_f32_e32 v26, 0xbfb8aa3b, v26
	v_mul_f32_e32 v19, v27, v19
	v_mul_f32_e32 v27, 0xbfb8aa3b, v27
	v_mul_f32_e32 v20, v28, v20
	v_mul_f32_e32 v28, 0xbfb8aa3b, v28
	v_mul_f32_e32 v21, v29, v21
	v_mul_f32_e32 v29, 0xbfb8aa3b, v29
	v_exp_f32_e32 v30, v30
	v_exp_f32_e32 v31, v31
	v_exp_f32_e32 v32, v32
	v_exp_f32_e32 v33, v33
	v_exp_f32_e32 v26, v26
	v_exp_f32_e32 v27, v27
	v_exp_f32_e32 v28, v28
	v_exp_f32_e32 v29, v29
	v_add_f32_e32 v30, 1.0, v30
	v_add_f32_e32 v31, 1.0, v31
	v_add_f32_e32 v32, 1.0, v32
	v_add_f32_e32 v33, 1.0, v33
	v_add_f32_e32 v26, 1.0, v26
	v_add_f32_e32 v27, 1.0, v27
	v_add_f32_e32 v28, 1.0, v28
	v_add_f32_e32 v29, 1.0, v29
	v_rcp_f32_e32 v30, v30
	v_rcp_f32_e32 v31, v31
	v_rcp_f32_e32 v32, v32
	v_rcp_f32_e32 v33, v33
	v_rcp_f32_e32 v26, v26
	v_rcp_f32_e32 v27, v27
	v_rcp_f32_e32 v28, v28
	v_rcp_f32_e32 v29, v29
	v_mul_f32_e32 v22, v22, v30
	v_mul_f32_e32 v23, v23, v31
	v_mul_f32_e32 v24, v24, v32
	v_mul_f32_e32 v25, v25, v33
	v_mul_f32_e32 v26, v18, v26
	v_mul_f32_e32 v27, v19, v27
	v_mul_f32_e32 v28, v20, v28
	v_mul_f32_e32 v21, v21, v29
	v_cvt_pkrtz_f16_f32 v18, v22, v23
	v_cvt_pkrtz_f16_f32 v19, v24, v25
	v_cvt_pkrtz_f16_f32 v20, v26, v27
	v_cvt_pkrtz_f16_f32 v21, v28, v21
	global_store_dwordx4 v[36:37], v[18:21], off
	s_nop 1
	v_mov_b32_e32 v18, v198
	v_add_u32_e32 v19, 0xb0, v146
	v_mad_i64_i32 v[20:21], s[8:9], v19, s58, v[114:115]
	v_lshl_add_u64 v[20:21], v[20:21], 0, v[116:117]
	v_pk_mul_f32 v[16:17], v[16:17], v[18:19] op_sel_hi:[1,0]
	v_pk_mul_f32 v[14:15], v[14:15], v[18:19] op_sel_hi:[1,0]
	v_pk_mul_f32 v[12:13], v[12:13], v[18:19] op_sel_hi:[1,0]
	v_pk_mul_f32 v[10:11], v[10:11], v[18:19] op_sel_hi:[1,0]
	v_pk_mul_f32 v[8:9], v[8:9], v[18:19] op_sel_hi:[1,0]
	v_pk_mul_f32 v[6:7], v[6:7], v[18:19] op_sel_hi:[1,0]
	v_pk_mul_f32 v[4:5], v[4:5], v[18:19] op_sel_hi:[1,0]
	v_pk_mul_f32 v[2:3], v[2:3], v[18:19] op_sel_hi:[1,0]
	v_mul_f32_e32 v6, v14, v6
	v_mul_f32_e32 v14, 0xbfb8aa3b, v14
	v_mul_f32_e32 v7, v15, v7
	v_mul_f32_e32 v15, 0xbfb8aa3b, v15
	v_mul_f32_e32 v8, v16, v8
	v_mul_f32_e32 v16, 0xbfb8aa3b, v16
	v_mul_f32_e32 v9, v17, v9
	v_mul_f32_e32 v17, 0xbfb8aa3b, v17
	v_mul_f32_e32 v2, v10, v2
	v_mul_f32_e32 v10, 0xbfb8aa3b, v10
	v_mul_f32_e32 v3, v11, v3
	v_mul_f32_e32 v11, 0xbfb8aa3b, v11
	v_mul_f32_e32 v4, v12, v4
	v_mul_f32_e32 v12, 0xbfb8aa3b, v12
	v_mul_f32_e32 v5, v13, v5
	v_mul_f32_e32 v13, 0xbfb8aa3b, v13
	v_exp_f32_e32 v14, v14
	v_exp_f32_e32 v15, v15
	v_exp_f32_e32 v16, v16
	v_exp_f32_e32 v17, v17
	v_exp_f32_e32 v10, v10
	v_exp_f32_e32 v11, v11
	v_exp_f32_e32 v12, v12
	v_exp_f32_e32 v13, v13
	v_add_f32_e32 v14, 1.0, v14
	v_add_f32_e32 v15, 1.0, v15
	v_add_f32_e32 v16, 1.0, v16
	v_add_f32_e32 v17, 1.0, v17
	v_add_f32_e32 v10, 1.0, v10
	v_add_f32_e32 v11, 1.0, v11
	v_add_f32_e32 v12, 1.0, v12
	v_add_f32_e32 v13, 1.0, v13
	v_rcp_f32_e32 v14, v14
	v_rcp_f32_e32 v15, v15
	v_rcp_f32_e32 v16, v16
	v_rcp_f32_e32 v17, v17
	v_rcp_f32_e32 v10, v10
	v_rcp_f32_e32 v11, v11
	v_rcp_f32_e32 v12, v12
	v_rcp_f32_e32 v13, v13
	v_mul_f32_e32 v6, v6, v14
	v_mul_f32_e32 v7, v7, v15
	v_mul_f32_e32 v8, v8, v16
	v_mul_f32_e32 v9, v9, v17
	v_mul_f32_e32 v10, v2, v10
	v_mul_f32_e32 v11, v3, v11
	v_mul_f32_e32 v12, v4, v12
	v_mul_f32_e32 v5, v5, v13
	v_cvt_pkrtz_f16_f32 v2, v6, v7
	v_cvt_pkrtz_f16_f32 v3, v8, v9
	v_cvt_pkrtz_f16_f32 v4, v10, v11
	v_cvt_pkrtz_f16_f32 v5, v12, v5
	global_store_dwordx4 v[20:21], v[2:5], off
	s_cbranch_vccnz .LBB0_1011
	s_andn2_b64 vcc, exec, s[0:1]
	s_cbranch_vccnz .LBB0_1010
	s_barrier
	s_branch .LBB0_1010
